# diff-attn: next-tile LDS writes and global prefetch woven between the QK MFMAs (both branch arms duplicated)
# speedup vs baseline: 1.1238x; 1.0070x over previous
; DI f4 mfma16(h8 a, h8 b, f4 c) { return __builtin_amdgcn_mfma_f32_16x16x32_f16(a, b, c, 0, 0, 0); }
; template <int DQK, bool BIAS>
; __device__ __forceinline__ void attn_pass(const hf* __restrict__ Q, int ldq, const hf* __restrict__ Kp, int ldk, const hf* __restrict__ VT,
;                                           int s0, int L, int q0, float scale_l2, const float* sBias, f4 (&oacc)[8][4], char* smem) {
;     ...
;   auto loadKV = [&](int kt) {
;     const int key0 = kt * 64;
; #pragma unroll
;     for (int i = 0; i < NKL; ++i) rk[i] = *(const u4*)(Kp + (size_t)(s0 + key0 + (tid >> 2)) * ldk + ((tid & 3) + 4 * i) * 8);
; #pragma unroll
;     for (int i = 0; i < 4; ++i) { int idx = tid + 256 * i, dv = idx >> 3, ch = idx & 7; rv[i] = *(const u4*)(VT + (size_t)dv * T_TOK + s0 + key0 + ch * 8); }
;   };
;   auto storeKV = [&](int st) {
;     hf* sK = sbase + st * A_STG; hf* sVT = sK + 64 * 104;
; #pragma unroll
;     for (int i = 0; i < NKL; ++i) *(u4*)(sK + (tid >> 2) * KS + (((tid & 3) ^ (((tid >> 4) ^ (tid >> 5)) & 1)) + 4 * i) * 8) = rk[i];
; #pragma unroll
;     for (int i = 0; i < 4; ++i) { int idx = tid + 256 * i, dv = idx >> 3, ch = idx & 7; *(u4*)(sVT + dv * 72 + ch * 8) = rv[i]; }
;     ...
;     for (int mk = 0; mk < 4; ++mk) {
;       h8 kf[NKS];
; #pragma unroll
;       for (int ks = 0; ks < NKS; ++ks) kf[ks] = *(const h8*)(sK + (mk * 16 + fr) * KS + ks * 32 + (fq ^ (((fr >> 2) ^ (fr >> 3)) & 1)) * 8);
; #pragma unroll
;       for (int nq = 0; nq < 4; ++nq) {
;         f4 a = {0.f, 0.f, 0.f, 0.f};
; #pragma unroll
;         for (int ks = 0; ks < NKS; ++ks) a = mfma16(kf[ks], qf[nq][ks], a);
;         sacc[mk][nq] = a;
;       }
;     }
;     if (kt + 1 < nkt) storeKV((kt + 1) & 1);
;     if (kt + 2 < nkt) loadKV(kt + 2);
.LBB0_1948:
	s_bitcmp1_b32 s16, 0
	s_cselect_b32 s17, 0x7c00, 0
	s_add_i32 s95, s17, 16
	v_add_u32_e32 v40, s95, v239
	v_lshl_add_u32 v36, v238, 1, v40
	v_add_u32_e32 v44, v40, v240
	ds_read_b128 v[32:35], v36
	ds_read_b128 v[36:39], v36 offset:64
	ds_read_b128 v[48:51], v44 offset:2304
	ds_read_b128 v[52:55], v44 offset:2368
	ds_read_b128 v[56:59], v44 offset:4608
	ds_read_b128 v[60:63], v44 offset:4672
	ds_read_b128 v[40:43], v44 offset:6912
	ds_read_b128 v[64:67], v44 offset:6976
	s_add_i32 s94, s16, 1
	s_waitcnt lgkmcnt(7)
	v_mfma_f32_16x16x32_f16 v[188:191], v[32:35], v[0:3], 0
	s_waitcnt lgkmcnt(6)
	v_mfma_f32_16x16x32_f16 v[188:191], v[36:39], v[4:7], v[188:191]
	v_mfma_f32_16x16x32_f16 v[156:159], v[32:35], v[16:19], 0
	v_mfma_f32_16x16x32_f16 v[172:175], v[32:35], v[8:11], 0
	v_mfma_f32_16x16x32_f16 v[156:159], v[36:39], v[20:23], v[156:159]
	v_mfma_f32_16x16x32_f16 v[124:127], v[32:35], v[24:27], 0
	v_mfma_f32_16x16x32_f16 v[172:175], v[36:39], v[12:15], v[172:175]
	v_mfma_f32_16x16x32_f16 v[124:127], v[36:39], v[28:31], v[124:127]
	s_cmp_ge_u32 s94, s73
	s_cbranch_scc1 .Lqk_noW
	s_waitcnt lgkmcnt(5)
	v_mfma_f32_16x16x32_f16 v[184:187], v[48:51], v[0:3], 0
	s_bitcmp1_b32 s94, 0
	s_cselect_b32 s17, 0x7c00, 0
	s_waitcnt lgkmcnt(4)
	v_mfma_f32_16x16x32_f16 v[184:187], v[52:55], v[4:7], v[184:187]
	s_add_i32 s17, s17, 16
	v_add3_u32 v68, s17, v211, v244
	v_mfma_f32_16x16x32_f16 v[168:171], v[48:51], v[8:11], 0
	s_waitcnt vmcnt(1)
	ds_write_b128 v68, a[200:203]
	v_mfma_f32_16x16x32_f16 v[168:171], v[52:55], v[12:15], v[168:171]
	s_waitcnt vmcnt(0)
	ds_write_b128 v68, a[204:207] offset:64
	v_mfma_f32_16x16x32_f16 v[152:155], v[48:51], v[16:19], 0
	v_add3_u32 v68, s17, v232, v210
	v_mfma_f32_16x16x32_f16 v[152:155], v[52:55], v[20:23], v[152:155]
	ds_write_b128 v68, a[192:195] offset:13312
	v_mfma_f32_16x16x32_f16 v[120:123], v[48:51], v[24:27], 0
	v_add3_u32 v68, s17, v234, v210
	v_mfma_f32_16x16x32_f16 v[120:123], v[52:55], v[28:31], v[120:123]
	ds_write_b128 v68, a[196:199] offset:13312
	s_waitcnt lgkmcnt(3)
	v_mfma_f32_16x16x32_f16 v[180:183], v[56:59], v[0:3], 0
	v_add3_u32 v68, s17, v235, v210
	s_waitcnt lgkmcnt(2)
	v_mfma_f32_16x16x32_f16 v[180:183], v[60:63], v[4:7], v[180:183]
	ds_write_b128 v68, a[208:211] offset:13312
	v_mfma_f32_16x16x32_f16 v[164:167], v[56:59], v[8:11], 0
	v_add3_u32 v68, s17, v236, v210
	v_mfma_f32_16x16x32_f16 v[164:167], v[60:63], v[12:15], v[164:167]
	ds_write_b128 v68, a[212:215] offset:13312
	s_branch .Lqk_joinW
.Lqk_noW:
	s_waitcnt lgkmcnt(5)
	v_mfma_f32_16x16x32_f16 v[184:187], v[48:51], v[0:3], 0
	s_waitcnt lgkmcnt(4)
	v_mfma_f32_16x16x32_f16 v[184:187], v[52:55], v[4:7], v[184:187]
	v_mfma_f32_16x16x32_f16 v[168:171], v[48:51], v[8:11], 0
	v_mfma_f32_16x16x32_f16 v[168:171], v[52:55], v[12:15], v[168:171]
	v_mfma_f32_16x16x32_f16 v[152:155], v[48:51], v[16:19], 0
	v_mfma_f32_16x16x32_f16 v[152:155], v[52:55], v[20:23], v[152:155]
	v_mfma_f32_16x16x32_f16 v[120:123], v[48:51], v[24:27], 0
	v_mfma_f32_16x16x32_f16 v[120:123], v[52:55], v[28:31], v[120:123]
	s_waitcnt lgkmcnt(3)
	v_mfma_f32_16x16x32_f16 v[180:183], v[56:59], v[0:3], 0
	s_waitcnt lgkmcnt(2)
	v_mfma_f32_16x16x32_f16 v[180:183], v[60:63], v[4:7], v[180:183]
	v_mfma_f32_16x16x32_f16 v[164:167], v[56:59], v[8:11], 0
	v_mfma_f32_16x16x32_f16 v[164:167], v[60:63], v[12:15], v[164:167]
.Lqk_joinW:
	s_add_i32 s16, s16, 2
	s_cmp_ge_u32 s16, s73
	s_cbranch_scc1 .Lqk_noL
	v_mfma_f32_16x16x32_f16 v[148:151], v[56:59], v[16:19], 0
	v_add_u32_e32 v68, s20, v231
	v_mad_i64_i32 v[68:69], s[16:17], v68, s35, v[220:221]
	v_mfma_f32_16x16x32_f16 v[148:151], v[60:63], v[20:23], v[148:151]
	s_lshl_b64 s[16:17], s[20:21], 1
	v_mfma_f32_16x16x32_f16 v[116:119], v[56:59], v[24:27], 0
	global_load_dwordx4 a[200:203], v[68:69], off
	s_waitcnt lgkmcnt(1)
	v_mfma_f32_16x16x32_f16 v[176:179], v[40:43], v[0:3], 0
	global_load_dwordx4 a[204:207], v[68:69], off offset:64
	s_waitcnt lgkmcnt(0)
	v_mfma_f32_16x16x32_f16 v[176:179], v[64:67], v[4:7], v[176:179]
	v_lshl_add_u64 v[68:69], v[212:213], 0, s[16:17]
	v_mfma_f32_16x16x32_f16 v[160:163], v[40:43], v[8:11], 0
	global_load_dwordx4 a[192:195], v[68:69], off
	v_mfma_f32_16x16x32_f16 v[160:163], v[64:67], v[12:15], v[160:163]
	v_lshl_add_u64 v[68:69], v[214:215], 0, s[16:17]
	v_mfma_f32_16x16x32_f16 v[144:147], v[40:43], v[16:19], 0
	global_load_dwordx4 a[196:199], v[68:69], off
	v_mfma_f32_16x16x32_f16 v[144:147], v[64:67], v[20:23], v[144:147]
	v_lshl_add_u64 v[68:69], v[216:217], 0, s[16:17]
	v_mfma_f32_16x16x32_f16 v[112:115], v[40:43], v[24:27], 0
	global_load_dwordx4 a[208:211], v[68:69], off
	v_mfma_f32_16x16x32_f16 v[116:119], v[60:63], v[28:31], v[116:119]
	v_lshl_add_u64 v[68:69], v[218:219], 0, s[16:17]
	v_mfma_f32_16x16x32_f16 v[112:115], v[64:67], v[28:31], v[112:115]
	global_load_dwordx4 a[212:215], v[68:69], off
	s_branch .LBB0_1952
.Lqk_noL:
	v_mfma_f32_16x16x32_f16 v[148:151], v[56:59], v[16:19], 0
	v_mfma_f32_16x16x32_f16 v[148:151], v[60:63], v[20:23], v[148:151]
	v_mfma_f32_16x16x32_f16 v[116:119], v[56:59], v[24:27], 0
	s_waitcnt lgkmcnt(1)
	v_mfma_f32_16x16x32_f16 v[176:179], v[40:43], v[0:3], 0
	s_waitcnt lgkmcnt(0)
	v_mfma_f32_16x16x32_f16 v[176:179], v[64:67], v[4:7], v[176:179]
	v_mfma_f32_16x16x32_f16 v[160:163], v[40:43], v[8:11], 0
	v_mfma_f32_16x16x32_f16 v[160:163], v[64:67], v[12:15], v[160:163]
	v_mfma_f32_16x16x32_f16 v[144:147], v[40:43], v[16:19], 0
	v_mfma_f32_16x16x32_f16 v[144:147], v[64:67], v[20:23], v[144:147]
	v_mfma_f32_16x16x32_f16 v[112:115], v[40:43], v[24:27], 0
	v_mfma_f32_16x16x32_f16 v[116:119], v[60:63], v[28:31], v[116:119]
	v_mfma_f32_16x16x32_f16 v[112:115], v[64:67], v[28:31], v[112:115]
